# prep/GLA-A items: write-through sc1 stores instead of L2 write-back release fence
# speedup vs baseline: 1.0625x; 1.0385x over previous
; __device__ __forceinline__ int opaque_tid() { int t = threadIdx.x; asm volatile("" : "+v"(t)); return t; }
; __device__ void gla_passA_item(const Params& p, int l, int item, unsigned char* ldsraw) {
;     ...
;   for (int e = tid; e < 2048; e += NT) {
;     const int k = e >> 6, v = e & 63;
;     float a = 0.f;
; #pragma unroll 8
;     for (int s = 0; s < 64; ++s) a += kd[s * 32 + k] * vs[s * 64 + v];
;     gS[e] = a;
;   }
;   if (tid < 32) gD[tid] = __expf(bc[63 * 32 + tid]);
;   __syncthreads();
; template <bool COOP>
; __global__ void __launch_bounds__(NT, 2) mega(Params p) {
;     ...
;             asm volatile("s_waitcnt vmcnt(0)" ::: "memory");
;             __syncthreads();
;             if (opaque_tid() == 0) {
;               __builtin_amdgcn_fence(__ATOMIC_RELEASE, "agent");
;               asm volatile("s_waitcnt vmcnt(0)" ::: "memory");
;               __hip_atomic_fetch_add(glaA_done, 1u, __ATOMIC_RELAXED, __HIP_MEMORY_SCOPE_AGENT);
;             }
.LBB0_565:
	v_add_u32_e32 v22, s12, v5
	ds_read2st64_b32 v[8:9], v7 offset1:1
	ds_read2st64_b32 v[10:11], v7 offset0:2 offset1:3
	ds_read2st64_b32 v[12:13], v7 offset0:4 offset1:5
	ds_read2st64_b32 v[14:15], v7 offset0:6 offset1:7
	ds_read2_b32 v[16:17], v22 offset1:32
	ds_read2_b32 v[18:19], v22 offset0:64 offset1:96
	ds_read2_b32 v[20:21], v22 offset0:128 offset1:160
	ds_read2_b32 v[22:23], v22 offset0:192 offset1:224
	s_addk_i32 s12, 0x400
	s_waitcnt lgkmcnt(3)
	v_fmac_f32_e32 v3, v16, v8
	v_fmac_f32_e32 v3, v17, v9
	s_waitcnt lgkmcnt(2)
	v_fmac_f32_e32 v3, v18, v10
	v_fmac_f32_e32 v3, v19, v11
	s_waitcnt lgkmcnt(1)
	v_fmac_f32_e32 v3, v20, v12
	v_fmac_f32_e32 v3, v21, v13
	s_waitcnt lgkmcnt(0)
	v_fmac_f32_e32 v3, v22, v14
	v_add_u32_e32 v7, 0x800, v7
	s_cmpk_eq_i32 s12, 0x2000
	v_fmac_f32_e32 v3, v23, v15
	s_cbranch_scc0 .LBB0_565
	v_ashrrev_i32_e32 v5, 31, v4
	v_lshl_add_u64 v[8:9], v[4:5], 2, s[6:7]
	s_movk_i32 s12, 0x5ff
	global_store_dword v[8:9], v3, off sc1
	v_add_u32_e32 v3, 0x200, v4
	v_cmp_lt_i32_e32 vcc, s12, v4
	s_or_b64 s[10:11], vcc, s[10:11]
	v_mov_b32_e32 v4, v3
	s_andn2_b64 exec, exec, s[10:11]
	s_cbranch_execnz .LBB0_564
.LBB0_567:
	s_or_b64 exec, exec, s[0:1]
	v_cmp_gt_i32_e32 vcc, 32, v2
	s_and_saveexec_b64 s[0:1], vcc
	s_cbranch_execz .LBB0_569
	v_lshl_add_u32 v0, v2, 2, v94
	ds_read_b32 v0, v0 offset:40832
	s_lshl_b64 s[6:7], s[8:9], 7
	v_readlane_b32 s8, v162, 29
	s_add_u32 s6, s8, s6
	v_readlane_b32 s8, v162, 30
	s_waitcnt lgkmcnt(0)
	v_mul_f32_e32 v0, 0x3fb8aa3b, v0
	v_exp_f32_e32 v0, v0
	s_addc_u32 s7, s8, s7
	v_ashrrev_i32_e32 v3, 31, v2
	v_lshl_add_u64 v[2:3], v[2:3], 2, s[6:7]
	global_store_dword v[2:3], v0, off sc1
.LBB0_569:
	s_or_b64 exec, exec, s[0:1]
	s_waitcnt vmcnt(63) expcnt(7) lgkmcnt(15)
	s_barrier
	s_waitcnt vmcnt(0)
	v_mov_b32_e32 v0, v68
	s_barrier
	s_nop 0
	v_cmp_eq_u32_e32 vcc, 0, v0
	s_and_saveexec_b64 s[0:1], vcc
	s_cbranch_execz .LBB0_572
	s_mov_b64 s[6:7], exec
	v_mbcnt_lo_u32_b32 v0, s6, 0
	s_nop 0
	s_waitcnt vmcnt(0)
	s_waitcnt vmcnt(0)
	v_mbcnt_hi_u32_b32 v0, s7, v0
	v_cmp_eq_u32_e32 vcc, 0, v0
	s_and_b64 s[8:9], exec, vcc
	s_mov_b64 exec, s[8:9]
	s_cbranch_execz .LBB0_572
	s_bcnt1_i32_b64 s6, s[6:7]
	v_mov_b32_e32 v0, s6
	global_atomic_add v1, v0, s[34:35] offset:160

; __device__ __forceinline__ u32 pack2(float lo, float hi) { return (u32)f2bf(lo) | ((u32)f2bf(hi) << 16); }
; __device__ __forceinline__ float wsum_u(float v) { return rdlane63(wsum_dpp63(v)); }
; __device__ void rwprep_items(const Params& p, int l, unsigned char* ldsraw, int it_begin, int it_end, int it_step) {
;     ...
;         r += (r1 - r) * mur; k += (k1 - k) * muk; v += (v1 - v) * muv;
;         const float xw = w0c + aw[tt];
;         const float lw = -softplus_f(-xw) - 0.5f;
;         const float dec = __expf(-__expf(lw));
;         const float xa = a0c + aa[tt];
;         const float asig = 1.f / (1.f + __expf(-xa));
;         const float kkr = k * kkc;
;         const float ssum = wsum_u(kkr * kkr);
;         const float kk = kkr * rsqrtf(fmaxf(ssum, 1e-12f));
;         const float kmod = k * (1.f + (asig - 1.f) * kac);
;         const size_t o = ((size_t)tok * 384 + c) * 3;
;         rwp[o] = __float_as_uint(dec);
;         rwp[o + 1] = pack2(kk, kk * asig);
;         rwp[o + 2] = pack2(kmod, r);
;         const float bsum = wsum_u(r * kmod * rkc);
;         if ((tid & 63) == 0) bon[(size_t)tok * 6 + (tid >> 6)] = bsum;
;         vy[(size_t)tok * 384 + c] = f2bf(v);
.LBB0_576:
	s_or_b64 exec, exec, s[0:1]
	v_lshlrev_b32_e32 v0, 16, v0
	v_sub_f32_e32 v5, v9, v0
	v_fmac_f32_e32 v0, v5, v49
	v_bfe_u32 v5, v0, 16, 1
	v_add3_u32 v0, v0, v5, s96
	v_lshl_add_u64 v[32:33], v[32:33], 1, s[88:89]
	global_store_short_d16_hi v[32:33], v0, off sc1

; __device__ __forceinline__ float wsum_u(float v) { return rdlane63(wsum_dpp63(v)); }
; __device__ void rwprep_items(const Params& p, int l, unsigned char* ldsraw, int it_begin, int it_end, int it_step) {
;     ...
;       for (int j = 0; j < 32; ++j) {
;         const float wu = w_up[j * 384 + c], au = a_up[j * 384 + c];
; #pragma unroll
;         for (int tt = 0; tt < 4; ++tt) {
;           aw[tt] += codes[tt * 64 + j] * wu;
;           aa[tt] += codes[tt * 64 + 32 + j] * au;
;         }
;       }
;       const float mur = mu[c], muk = mu[384 + c], muv = mu[768 + c];
;       const float w0c = w0[c], a0c = a0[c], kkc = k_k[c], kac = k_a[c], rkc = r_k[c];
; #pragma unroll
;       for (int tt = 0; tt < 4; ++tt) {
;         const int tok = tok0 + tt;
;         float r = pr_[tt + 1], k = pk_[tt + 1], v = pv_[tt + 1];
;         const float r1 = pr_[tt], k1 = pk_[tt], v1 = pv_[tt];
;         r += (r1 - r) * mur; k += (k1 - k) * muk; v += (v1 - v) * muv;
;         const float xw = w0c + aw[tt];
;         const float lw = -softplus_f(-xw) - 0.5f;
;         const float dec = __expf(-__expf(lw));
;         const float xa = a0c + aa[tt];
;         const float asig = 1.f / (1.f + __expf(-xa));
;         const float kkr = k * kkc;
;         const float ssum = wsum_u(kkr * kkr);
;         const float kk = kkr * rsqrtf(fmaxf(ssum, 1e-12f));
.LBB0_588:
	v_add_u32_e32 v49, s0, v2
	v_add_u32_e32 v54, 0x180, v49
	global_load_dword v50, v[42:43], off
	global_load_dword v66, v[36:37], off
	v_add_u32_e32 v56, 0x300, v49
	v_add_u32_e32 v62, 0x480, v49
	v_ashrrev_i32_e32 v55, 31, v54
	v_ashrrev_i32_e32 v57, 31, v56
	v_ashrrev_i32_e32 v63, 31, v62
	v_lshlrev_b64 v[54:55], 2, v[54:55]
	v_lshlrev_b64 v[56:57], 2, v[56:57]
	v_lshlrev_b64 v[62:63], 2, v[62:63]
	v_lshl_add_u64 v[64:65], s[94:95], 0, v[54:55]
	v_lshl_add_u64 v[54:55], s[90:91], 0, v[54:55]
	v_lshl_add_u64 v[70:71], s[94:95], 0, v[56:57]
	v_lshl_add_u64 v[56:57], s[90:91], 0, v[56:57]
	v_lshl_add_u64 v[72:73], s[94:95], 0, v[62:63]
	v_lshl_add_u64 v[62:63], s[90:91], 0, v[62:63]
	global_load_dword v86, v[64:65], off
	global_load_dword v112, v[54:55], off
	global_load_dword v114, v[70:71], off
	global_load_dword v116, v[56:57], off
	global_load_dword v118, v[72:73], off
	global_load_dword v120, v[62:63], off
	v_mov_b32_e32 v49, s1
	ds_read_b128 v[54:57], v49
	ds_read_b128 v[62:65], v49 offset:128
	ds_read_b128 v[70:73], v49 offset:256
	ds_read_b128 v[74:77], v49 offset:384
	ds_read_b128 v[78:81], v49 offset:512
	ds_read_b128 v[82:85], v49 offset:640
	ds_read_b128 v[104:107], v49 offset:768
	ds_read_b128 v[108:111], v49 offset:896
	s_waitcnt lgkmcnt(7)
	v_mov_b32_e32 v122, v54
	s_waitcnt lgkmcnt(5)
	v_mov_b32_e32 v123, v70
	v_mov_b32_e32 v124, v62
	s_waitcnt lgkmcnt(4)
	v_mov_b32_e32 v125, v74
	s_waitcnt lgkmcnt(3)
	v_mov_b32_e32 v126, v78
	s_waitcnt lgkmcnt(1)
	v_mov_b32_e32 v127, v104
	v_mov_b32_e32 v128, v82
	s_waitcnt lgkmcnt(0)
	v_mov_b32_e32 v129, v108
	v_mov_b32_e32 v70, v55
	v_mov_b32_e32 v74, v63
	v_mov_b32_e32 v104, v79
	v_mov_b32_e32 v108, v83
	v_mov_b32_e32 v54, v56
	v_mov_b32_e32 v55, v72
	v_mov_b32_e32 v62, v64
	v_mov_b32_e32 v63, v76
	v_mov_b32_e32 v78, v80
	v_mov_b32_e32 v79, v106
	v_mov_b32_e32 v82, v84
	v_mov_b32_e32 v83, v110
	s_addk_i32 s0, 0x600
	s_add_i32 s1, s1, 16
	v_mov_b32_e32 v72, v57
	v_mov_b32_e32 v76, v65
	v_mov_b32_e32 v106, v81
	v_mov_b32_e32 v110, v85
	v_lshl_add_u64 v[42:43], v[42:43], 0, s[92:93]
	v_lshl_add_u64 v[36:37], v[36:37], 0, s[92:93]
	s_cmpk_eq_i32 s0, 0x3000
	s_waitcnt vmcnt(7)
	v_pk_fma_f32 v[38:39], v[50:51], v[122:123], v[38:39] op_sel_hi:[0,1,1]
	s_waitcnt vmcnt(6)
	v_pk_fma_f32 v[40:41], v[66:67], v[124:125], v[40:41] op_sel_hi:[0,1,1]
	v_pk_fma_f32 v[34:35], v[50:51], v[126:127], v[34:35] op_sel_hi:[0,1,1]
	v_pk_fma_f32 v[32:33], v[66:67], v[128:129], v[32:33] op_sel_hi:[0,1,1]
	s_waitcnt vmcnt(5)
	v_pk_fma_f32 v[38:39], v[86:87], v[70:71], v[38:39] op_sel_hi:[0,1,1]
	s_waitcnt vmcnt(4)
	v_pk_fma_f32 v[40:41], v[112:113], v[74:75], v[40:41] op_sel_hi:[0,1,1]
	v_pk_fma_f32 v[34:35], v[86:87], v[104:105], v[34:35] op_sel_hi:[0,1,1]
	v_pk_fma_f32 v[32:33], v[112:113], v[108:109], v[32:33] op_sel_hi:[0,1,1]
	s_waitcnt vmcnt(3)
	v_pk_fma_f32 v[38:39], v[114:115], v[54:55], v[38:39] op_sel_hi:[0,1,1]
	s_waitcnt vmcnt(2)
	v_pk_fma_f32 v[40:41], v[116:117], v[62:63], v[40:41] op_sel_hi:[0,1,1]
	v_pk_fma_f32 v[34:35], v[114:115], v[78:79], v[34:35] op_sel_hi:[0,1,1]
	v_pk_fma_f32 v[32:33], v[116:117], v[82:83], v[32:33] op_sel_hi:[0,1,1]
	s_waitcnt vmcnt(1)
	v_pk_fma_f32 v[38:39], v[118:119], v[72:73], v[38:39] op_sel_hi:[0,1,1]
	s_waitcnt vmcnt(0)
	v_pk_fma_f32 v[40:41], v[120:121], v[76:77], v[40:41] op_sel_hi:[0,1,1]
	v_pk_fma_f32 v[34:35], v[118:119], v[106:107], v[34:35] op_sel_hi:[0,1,1]
	v_pk_fma_f32 v[32:33], v[120:121], v[110:111], v[32:33] op_sel_hi:[0,1,1]
	s_cbranch_scc0 .LBB0_588
	global_load_dword v37, v[12:13], off
	global_load_dword v57, v[14:15], off
	global_load_dword v56, v[16:17], off
	global_load_dword v55, v[12:13], off offset:1536
	global_load_dword v36, v[18:19], off
	global_load_dword v54, v[20:21], off
	global_load_dword v50, v[22:23], off
	global_load_dword v49, v[12:13], off offset:3072
	v_lshlrev_b32_e32 v62, 16, v45
	v_lshlrev_b32_e32 v43, 16, v44
	v_mad_i64_i32 v[44:45], s[0:1], s25, v98, v[2:3]
	v_sub_f32_e32 v42, v61, v43
	v_sub_f32_e32 v63, v60, v62
	v_mad_u64_u32 v[60:61], s[0:1], v44, 12, s[84:85]
	s_mov_b32 s0, 0xbfb8aa3b
	v_mad_i32_i24 v61, v45, 12, v61
	s_waitcnt vmcnt(7)
	v_fma_f32 v42, v42, v37, v43
	s_waitcnt vmcnt(6)
	v_add_f32_e32 v38, v38, v57
	s_waitcnt vmcnt(5)
	v_add_f32_e32 v40, v40, v56
	v_mul_f32_e32 v40, 0xbfb8aa3b, v40
	s_waitcnt vmcnt(4)
	v_fma_f32 v65, v63, v55, v62
	v_max_f32_e64 v63, -v38, 0
	v_mul_f32_e64 v38, |v38|, s0
	v_exp_f32_e32 v40, v40
	s_waitcnt vmcnt(3)
	v_mul_f32_e32 v64, v65, v36
	v_exp_f32_e32 v38, v38
	v_mul_f32_e32 v67, v64, v64
	v_and_b32_sdwa v66, v42, v93 dst_sel:DWORD dst_unused:UNUSED_PAD src0_sel:WORD_1 src1_sel:DWORD
	v_add3_u32 v66, v42, v66, s96
	v_mov_b32_dpp v67, v67 quad_perm:[1,0,3,2] row_mask:0xf bank_mask:0xf bound_ctrl:1
	v_fmac_f32_e32 v67, v64, v64
	v_add_f32_e32 v40, 1.0, v40
	v_and_b32_e32 v70, 0xffff0000, v66
	v_add_f32_dpp v66, v67, v67 quad_perm:[2,3,0,1] row_mask:0xf bank_mask:0xf bound_ctrl:1
	v_add_f32_e32 v38, 1.0, v38
	v_div_scale_f32 v67, s[0:1], v40, v40, 1.0
	v_add_f32_dpp v66, v66, v66 row_half_mirror row_mask:0xf bank_mask:0xf bound_ctrl:1
	v_cmp_gt_f32_e64 s[0:1], s82, v38
	v_rcp_f32_e32 v74, v67
	v_add_f32_dpp v66, v66, v66 row_ror:8 row_mask:0xf bank_mask:0xf bound_ctrl:1
	v_cndmask_b32_e64 v72, 0, 32, s[0:1]
	v_ldexp_f32 v38, v38, v72
	v_add_f32_dpp v66, v66, v66 row_bcast:15 row_mask:0xf bank_mask:0xf bound_ctrl:1
	v_log_f32_e32 v38, v38
	v_cndmask_b32_e64 v73, 0, v95, s[0:1]
	v_add_f32_dpp v66, v66, v66 row_bcast:31 row_mask:0xf bank_mask:0xf bound_ctrl:1
	v_fma_f32 v72, -v67, v74, 1.0
	v_readlane_b32 s0, v66, 63
	v_div_scale_f32 v71, vcc, 1.0, v40, 1.0
	s_nop 0
	v_max_f32_e64 v66, s0, s0
	v_max_f32_e32 v66, 0x2b8cbccc, v66
	v_fmac_f32_e32 v74, v72, v74
	v_rsq_f32_e32 v66, v66
	v_mul_f32_e32 v72, 0x3f317217, v38
	v_mul_f32_e32 v75, v71, v74
	v_fma_f32 v72, v38, s20, -v72
	v_fma_f32 v76, -v67, v75, v71
	v_fmac_f32_e32 v72, 0x3377d1cf, v38
	v_fmac_f32_e32 v75, v76, v74
	v_fmac_f32_e32 v72, 0x3f317217, v38
	v_fma_f32 v67, -v67, v75, v71
	v_cmp_lt_f32_e64 s[0:1], |v38|, s21
	v_mul_f32_e32 v64, v64, v66
	v_div_fmas_f32 v66, v67, v74, v75
	v_cndmask_b32_e64 v38, v38, v72, s[0:1]
	v_sub_f32_e32 v38, v38, v73
	v_div_fixup_f32 v66, v66, v40, 1.0
	v_and_b32_sdwa v67, v64, v93 dst_sel:DWORD dst_unused:UNUSED_PAD src0_sel:WORD_1 src1_sel:DWORD
	v_add_f32_e32 v38, v63, v38
	v_add_f32_e32 v63, -1.0, v66
	v_add3_u32 v40, v64, v67, s96
	v_sub_f32_e32 v38, -0.5, v38
	s_waitcnt vmcnt(2)
; __device__ __forceinline__ u32 pack2(float lo, float hi) { return (u32)f2bf(lo) | ((u32)f2bf(hi) << 16); }
; __device__ __forceinline__ float wsum_u(float v) { return rdlane63(wsum_dpp63(v)); }
; __device__ void rwprep_items(const Params& p, int l, unsigned char* ldsraw, int it_begin, int it_end, int it_step) {
;     ...
;       for (int tt = 0; tt < 4; ++tt) {
;         const int tok = tok0 + tt;
;         float r = pr_[tt + 1], k = pk_[tt + 1], v = pv_[tt + 1];
;         const float r1 = pr_[tt], k1 = pk_[tt], v1 = pv_[tt];
;         r += (r1 - r) * mur; k += (k1 - k) * muk; v += (v1 - v) * muv;
;         const float xw = w0c + aw[tt];
;         const float lw = -softplus_f(-xw) - 0.5f;
;         const float dec = __expf(-__expf(lw));
;         const float xa = a0c + aa[tt];
;         const float asig = 1.f / (1.f + __expf(-xa));
;         const float kkr = k * kkc;
;         const float ssum = wsum_u(kkr * kkr);
;         const float kk = kkr * rsqrtf(fmaxf(ssum, 1e-12f));
;         const float kmod = k * (1.f + (asig - 1.f) * kac);
;         const size_t o = ((size_t)tok * 384 + c) * 3;
;         rwp[o] = __float_as_uint(dec);
;         rwp[o + 1] = pack2(kk, kk * asig);
;         rwp[o + 2] = pack2(kmod, r);
;         const float bsum = wsum_u(r * kmod * rkc);
;         if ((tid & 63) == 0) bon[(size_t)tok * 6 + (tid >> 6)] = bsum;
;         vy[(size_t)tok * 384 + c] = f2bf(v);
;       }
	v_fma_f32 v67, v54, v63, 1.0
	v_mul_f32_e32 v38, 0x3fb8aa3b, v38
	v_pk_mul_f32 v[64:65], v[66:67], v[64:65]
	v_exp_f32_e32 v38, v38
	v_and_b32_sdwa v63, v65, v93 dst_sel:DWORD dst_unused:UNUSED_PAD src0_sel:WORD_1 src1_sel:DWORD
	v_mul_f32_e32 v42, v42, v65
	v_and_b32_sdwa v66, v64, v93 dst_sel:DWORD dst_unused:UNUSED_PAD src0_sel:WORD_1 src1_sel:DWORD
	v_add3_u32 v63, v65, v63, s96
	s_waitcnt vmcnt(1)
	v_mul_f32_e32 v65, v50, v42
	v_add3_u32 v64, v64, v66, s96
	v_or_b32_sdwa v66, v63, v70 dst_sel:DWORD dst_unused:UNUSED_PAD src0_sel:WORD_1 src1_sel:DWORD
	v_mov_b32_dpp v63, v65 quad_perm:[1,0,3,2] row_mask:0xf bank_mask:0xf bound_ctrl:1
	v_and_b32_e32 v64, 0xffff0000, v64
	v_fmac_f32_e32 v63, v50, v42
	v_or_b32_sdwa v65, v64, v40 dst_sel:DWORD dst_unused:UNUSED_PAD src0_sel:DWORD src1_sel:WORD_1
	v_mul_f32_e32 v38, 0xbfb8aa3b, v38
	v_add_f32_dpp v40, v63, v63 quad_perm:[2,3,0,1] row_mask:0xf bank_mask:0xf bound_ctrl:1
	v_exp_f32_e32 v64, v38
	global_store_dwordx3 v[60:61], v[64:66], off sc1
	v_add_f32_dpp v38, v40, v40 row_half_mirror row_mask:0xf bank_mask:0xf bound_ctrl:1
	s_nop 1
	v_add_f32_dpp v38, v38, v38 row_ror:8 row_mask:0xf bank_mask:0xf bound_ctrl:1
	s_nop 1
	v_add_f32_dpp v38, v38, v38 row_bcast:15 row_mask:0xf bank_mask:0xf bound_ctrl:1
	s_nop 1
	v_add_f32_dpp v38, v38, v38 row_bcast:31 row_mask:0xf bank_mask:0xf bound_ctrl:1
	s_nop 0
	v_readlane_b32 s26, v38, 63
	s_and_saveexec_b64 s[0:1], s[12:13]
	s_cbranch_execz .LBB0_591
	v_mad_i64_i32 v[60:61], s[28:29], s25, 24, v[24:25]
	v_mov_b32_e32 v38, s26
	global_store_dword v[60:61], v38, off sc1
.LBB0_591:
	s_or_b64 exec, exec, s[0:1]
	v_lshlrev_b32_e32 v38, 16, v47
	v_add_f32_e32 v39, v39, v57
	s_mov_b32 s0, 0xbfb8aa3b
	v_sub_f32_e32 v40, v46, v38
	v_mul_f32_e64 v46, |v39|, s0
	v_exp_f32_e32 v46, v46
	s_waitcnt vmcnt(1)
	v_fma_f32 v40, v40, v49, v38
	v_lshlrev_b32_e32 v47, 16, v58
	v_bfe_u32 v58, v40, 16, 1
	v_add_f32_e32 v46, 1.0, v46
	v_cmp_gt_f32_e32 vcc, s82, v46
	v_add3_u32 v40, v40, v58, s96
	v_lshl_add_u64 v[44:45], v[44:45], 1, s[88:89]
	v_cndmask_b32_e64 v58, 0, 32, vcc
	v_ldexp_f32 v46, v46, v58
	v_log_f32_e32 v46, v46
	global_store_short_d16_hi v[44:45], v40, off sc1
	v_add_f32_e32 v41, v41, v56
	v_mul_f32_e32 v41, 0xbfb8aa3b, v41
	v_mul_f32_e32 v44, 0x3f317217, v46
	v_fma_f32 v44, v46, s20, -v44
	v_fmac_f32_e32 v44, 0x3377d1cf, v46
	v_fmac_f32_e32 v44, 0x3f317217, v46
	v_cmp_lt_f32_e64 s[0:1], |v46|, s21
	v_cndmask_b32_e32 v45, 0, v95, vcc
	v_exp_f32_e32 v41, v41
	v_cndmask_b32_e64 v44, v46, v44, s[0:1]
	v_max_f32_e64 v39, -v39, 0
	v_sub_f32_e32 v44, v44, v45
	v_add_f32_e32 v39, v39, v44
	v_sub_f32_e32 v39, -0.5, v39
	v_mul_f32_e32 v39, 0x3fb8aa3b, v39
	v_add_f32_e32 v41, 1.0, v41
	v_exp_f32_e32 v39, v39
	v_div_scale_f32 v45, s[0:1], v41, v41, 1.0
	v_rcp_f32_e32 v58, v45
	v_mul_f32_e32 v39, 0xbfb8aa3b, v39
	v_lshlrev_b32_e32 v42, 16, v59
	v_exp_f32_e32 v44, v39
	v_fma_f32 v39, -v45, v58, 1.0
	v_sub_f32_e32 v40, v62, v42
	v_fmac_f32_e32 v58, v39, v58
	v_div_scale_f32 v39, vcc, 1.0, v41, 1.0
	v_mul_f32_e32 v46, v40, v55
	v_mul_f32_e32 v40, v39, v58
	v_fma_f32 v59, -v45, v40, v39
	v_fmac_f32_e32 v40, v59, v58
	v_fma_f32 v39, -v45, v40, v39
	v_div_fmas_f32 v39, v39, v58, v40
	v_pk_add_f32 v[60:61], v[46:47], v[42:43]
	v_pk_add_f32 v[62:63], v[42:43], v[46:47] neg_lo:[0,1] neg_hi:[0,1]
	v_div_fixup_f32 v58, v39, v41, 1.0
	v_mov_b32_e32 v61, v63
	v_add_f32_e32 v39, -1.0, v58
	v_pk_mul_f32 v[62:63], v[60:61], v[36:37]
	v_fma_f32 v59, v54, v39, 1.0
	v_mul_f32_e32 v39, v62, v62
	v_mad_i64_i32 v[40:41], s[0:1], s24, v98, v[2:3]
	s_nop 0
	v_mov_b32_dpp v39, v39 quad_perm:[1,0,3,2] row_mask:0xf bank_mask:0xf bound_ctrl:1
	v_fmac_f32_e32 v39, v62, v62
	s_nop 1
	v_add_f32_dpp v39, v39, v39 quad_perm:[2,3,0,1] row_mask:0xf bank_mask:0xf bound_ctrl:1
	s_nop 1
	v_add_f32_dpp v39, v39, v39 row_half_mirror row_mask:0xf bank_mask:0xf bound_ctrl:1
	s_nop 1
	v_add_f32_dpp v39, v39, v39 row_ror:8 row_mask:0xf bank_mask:0xf bound_ctrl:1
	s_nop 1
	v_add_f32_dpp v39, v39, v39 row_bcast:15 row_mask:0xf bank_mask:0xf bound_ctrl:1
	s_nop 1
	v_add_f32_dpp v39, v39, v39 row_bcast:31 row_mask:0xf bank_mask:0xf bound_ctrl:1
	s_nop 0
	v_readlane_b32 s0, v39, 63
	s_nop 1
	v_max_f32_e64 v39, s0, s0
	v_max_f32_e32 v39, 0x2b8cbccc, v39
	v_rsq_f32_e32 v46, v39
	v_mad_u64_u32 v[64:65], s[0:1], v40, 12, s[84:85]
	v_mad_i32_i24 v65, v41, 12, v65
	v_pk_mul_f32 v[62:63], v[62:63], v[46:47]
	v_pk_fma_f32 v[66:67], v[60:61], v[36:37], v[46:47]
	v_mov_b32_e32 v63, v60
	v_pk_mul_f32 v[58:59], v[58:59], v[62:63]
	v_and_b32_sdwa v45, v67, v93 dst_sel:DWORD dst_unused:UNUSED_PAD src0_sel:WORD_1 src1_sel:DWORD
	v_and_b32_sdwa v39, v59, v93 dst_sel:DWORD dst_unused:UNUSED_PAD src0_sel:WORD_1 src1_sel:DWORD
	v_and_b32_sdwa v43, v58, v93 dst_sel:DWORD dst_unused:UNUSED_PAD src0_sel:WORD_1 src1_sel:DWORD
	v_add3_u32 v45, v67, v45, s96
	v_add3_u32 v39, v59, v39, s96
	v_add3_u32 v43, v58, v43, s96
	v_and_b32_sdwa v46, v62, v93 dst_sel:DWORD dst_unused:UNUSED_PAD src0_sel:WORD_1 src1_sel:DWORD
	v_and_b32_e32 v45, 0xffff0000, v45
	v_and_b32_e32 v43, 0xffff0000, v43
	v_add3_u32 v58, v62, v46, s96
	v_or_b32_sdwa v46, v39, v45 dst_sel:DWORD dst_unused:UNUSED_PAD src0_sel:WORD_1 src1_sel:DWORD
	v_mul_f32_e32 v39, v67, v59
	v_or_b32_sdwa v45, v43, v58 dst_sel:DWORD dst_unused:UNUSED_PAD src0_sel:DWORD src1_sel:WORD_1
	v_mul_f32_e32 v43, v50, v39
	global_store_dwordx3 v[64:65], v[44:46], off sc1
	s_nop 0
	v_mov_b32_dpp v43, v43 quad_perm:[1,0,3,2] row_mask:0xf bank_mask:0xf bound_ctrl:1
	v_fmac_f32_e32 v43, v50, v39
	s_nop 1
	v_add_f32_dpp v39, v43, v43 quad_perm:[2,3,0,1] row_mask:0xf bank_mask:0xf bound_ctrl:1
	s_nop 1
	v_add_f32_dpp v39, v39, v39 row_half_mirror row_mask:0xf bank_mask:0xf bound_ctrl:1
	s_nop 1
	v_add_f32_dpp v39, v39, v39 row_ror:8 row_mask:0xf bank_mask:0xf bound_ctrl:1
	s_nop 1
	v_add_f32_dpp v39, v39, v39 row_bcast:15 row_mask:0xf bank_mask:0xf bound_ctrl:1
	s_nop 1
	v_add_f32_dpp v39, v39, v39 row_bcast:31 row_mask:0xf bank_mask:0xf bound_ctrl:1
	s_nop 0
	v_readlane_b32 s25, v39, 63
	s_and_saveexec_b64 s[0:1], s[12:13]
	s_cbranch_execz .LBB0_593
	v_mad_i64_i32 v[44:45], s[26:27], s24, 24, v[24:25]
	v_mov_b32_e32 v39, s25
	global_store_dword v[44:45], v39, off sc1
; __device__ __forceinline__ u32 pack2(float lo, float hi) { return (u32)f2bf(lo) | ((u32)f2bf(hi) << 16); }
; __device__ __forceinline__ float wsum_u(float v) { return rdlane63(wsum_dpp63(v)); }
; __device__ void rwprep_items(const Params& p, int l, unsigned char* ldsraw, int it_begin, int it_end, int it_step) {
;     ...
;       for (int tt = 0; tt < 4; ++tt) {
;         const int tok = tok0 + tt;
;         float r = pr_[tt + 1], k = pk_[tt + 1], v = pv_[tt + 1];
;         const float r1 = pr_[tt], k1 = pk_[tt], v1 = pv_[tt];
;         r += (r1 - r) * mur; k += (k1 - k) * muk; v += (v1 - v) * muv;
;         const float xw = w0c + aw[tt];
;         const float lw = -softplus_f(-xw) - 0.5f;
;         const float dec = __expf(-__expf(lw));
;         const float xa = a0c + aa[tt];
;         const float asig = 1.f / (1.f + __expf(-xa));
;         const float kkr = k * kkc;
;         const float ssum = wsum_u(kkr * kkr);
;         const float kk = kkr * rsqrtf(fmaxf(ssum, 1e-12f));
;         const float kmod = k * (1.f + (asig - 1.f) * kac);
;         const size_t o = ((size_t)tok * 384 + c) * 3;
;         rwp[o] = __float_as_uint(dec);
;         rwp[o + 1] = pack2(kk, kk * asig);
;         rwp[o + 2] = pack2(kmod, r);
;         const float bsum = wsum_u(r * kmod * rkc);
;         if ((tid & 63) == 0) bon[(size_t)tok * 6 + (tid >> 6)] = bsum;
;         vy[(size_t)tok * 384 + c] = f2bf(v);
;       }
.LBB0_593:
	s_or_b64 exec, exec, s[0:1]
	v_add_f32_e32 v34, v34, v57
	s_mov_b32 s25, 0xbfb8aa3b
	v_lshlrev_b32_e32 v44, 16, v53
	v_mul_f32_e64 v46, |v34|, s25
	v_sub_f32_e32 v38, v38, v44
	v_exp_f32_e32 v46, v46
	v_fma_f32 v38, v38, v49, v44
	v_bfe_u32 v45, v38, 16, 1
	v_add3_u32 v38, v38, v45, s96
	v_lshl_add_u64 v[40:41], v[40:41], 1, s[88:89]
	global_store_short_d16_hi v[40:41], v38, off sc1
	v_add_f32_e32 v38, 1.0, v46
	v_cmp_gt_f32_e32 vcc, s82, v38
	v_lshlrev_b32_e32 v39, 16, v51
	v_add_f32_e32 v32, v32, v56
	v_cndmask_b32_e64 v40, 0, 32, vcc
	v_ldexp_f32 v38, v38, v40
	v_log_f32_e32 v38, v38
	v_sub_f32_e32 v40, v47, v39
	v_fma_f32 v45, v40, v37, v39
	v_mul_f32_e32 v32, 0xbfb8aa3b, v32
	v_mul_f32_e32 v40, 0x3f317217, v38
	v_fma_f32 v40, v38, s20, -v40
	v_fmac_f32_e32 v40, 0x3377d1cf, v38
	v_fmac_f32_e32 v40, 0x3f317217, v38
	v_cmp_lt_f32_e64 s[0:1], |v38|, s21
	v_exp_f32_e32 v32, v32
	v_max_f32_e64 v34, -v34, 0
	v_cndmask_b32_e64 v38, v38, v40, s[0:1]
	v_cndmask_b32_e32 v40, 0, v95, vcc
	v_sub_f32_e32 v38, v38, v40
	v_add_f32_e32 v34, v34, v38
	v_sub_f32_e32 v34, -0.5, v34
	v_mul_f32_e32 v34, 0x3fb8aa3b, v34
	v_add_f32_e32 v32, 1.0, v32
	v_exp_f32_e32 v34, v34
	v_div_scale_f32 v38, s[0:1], v32, v32, 1.0
	v_rcp_f32_e32 v40, v38
	v_mul_f32_e32 v34, 0xbfb8aa3b, v34
	v_exp_f32_e32 v58, v34
	v_lshlrev_b32_e32 v43, 16, v52
	v_fma_f32 v34, -v38, v40, 1.0
	v_fmac_f32_e32 v40, v34, v40
	v_div_scale_f32 v34, vcc, 1.0, v32, 1.0
	v_mul_f32_e32 v41, v34, v40
	v_fma_f32 v46, -v38, v41, v34
	v_fmac_f32_e32 v41, v46, v40
	v_fma_f32 v34, -v38, v41, v34
	v_div_fmas_f32 v34, v34, v40, v41
	v_sub_f32_e32 v42, v42, v43
	v_div_fixup_f32 v46, v34, v32, 1.0
	v_add_f32_e32 v32, -1.0, v46
	v_fma_f32 v53, v42, v55, v43
	v_fma_f32 v47, v54, v32, 1.0
	v_mul_f32_e32 v32, v53, v36
	v_mul_f32_e32 v34, v32, v32
	v_mad_i64_i32 v[40:41], s[0:1], s23, v98, v[2:3]
	s_nop 0
	v_mov_b32_dpp v34, v34 quad_perm:[1,0,3,2] row_mask:0xf bank_mask:0xf bound_ctrl:1
	v_fmac_f32_e32 v34, v32, v32
	v_and_b32_sdwa v38, v45, v93 dst_sel:DWORD dst_unused:UNUSED_PAD src0_sel:WORD_1 src1_sel:DWORD
	v_add3_u32 v38, v45, v38, s96
	v_add_f32_dpp v34, v34, v34 quad_perm:[2,3,0,1] row_mask:0xf bank_mask:0xf bound_ctrl:1
	v_and_b32_e32 v38, 0xffff0000, v38
	s_nop 0
	v_add_f32_dpp v34, v34, v34 row_half_mirror row_mask:0xf bank_mask:0xf bound_ctrl:1
	s_nop 1
	v_add_f32_dpp v34, v34, v34 row_ror:8 row_mask:0xf bank_mask:0xf bound_ctrl:1
	s_nop 1
	v_add_f32_dpp v34, v34, v34 row_bcast:15 row_mask:0xf bank_mask:0xf bound_ctrl:1
	s_nop 1
	v_add_f32_dpp v34, v34, v34 row_bcast:31 row_mask:0xf bank_mask:0xf bound_ctrl:1
	s_nop 0
	v_readlane_b32 s0, v34, 63
	s_nop 1
	v_max_f32_e64 v34, s0, s0
	v_max_f32_e32 v34, 0x2b8cbccc, v34
	v_rsq_f32_e32 v34, v34
	v_mad_u64_u32 v[62:63], s[0:1], v40, 12, s[84:85]
	v_mad_i32_i24 v63, v41, 12, v63
	v_mul_f32_e32 v52, v32, v34
	v_pk_mul_f32 v[46:47], v[46:47], v[52:53]
	v_and_b32_sdwa v42, v52, v93 dst_sel:DWORD dst_unused:UNUSED_PAD src0_sel:WORD_1 src1_sel:DWORD
	v_and_b32_sdwa v32, v47, v93 dst_sel:DWORD dst_unused:UNUSED_PAD src0_sel:WORD_1 src1_sel:DWORD
	v_and_b32_sdwa v34, v46, v93 dst_sel:DWORD dst_unused:UNUSED_PAD src0_sel:WORD_1 src1_sel:DWORD
	v_add3_u32 v32, v47, v32, s96
	v_add3_u32 v34, v46, v34, s96
	v_and_b32_e32 v34, 0xffff0000, v34
	v_add3_u32 v42, v52, v42, s96
	v_or_b32_sdwa v60, v32, v38 dst_sel:DWORD dst_unused:UNUSED_PAD src0_sel:WORD_1 src1_sel:DWORD
	v_mul_f32_e32 v32, v45, v47
	v_or_b32_sdwa v59, v34, v42 dst_sel:DWORD dst_unused:UNUSED_PAD src0_sel:DWORD src1_sel:WORD_1
	v_mul_f32_e32 v34, v50, v32
	global_store_dwordx3 v[62:63], v[58:60], off sc1
	s_nop 0
	v_mov_b32_dpp v34, v34 quad_perm:[1,0,3,2] row_mask:0xf bank_mask:0xf bound_ctrl:1
	v_fmac_f32_e32 v34, v50, v32
	s_nop 1
	v_add_f32_dpp v32, v34, v34 quad_perm:[2,3,0,1] row_mask:0xf bank_mask:0xf bound_ctrl:1
	s_nop 1
	v_add_f32_dpp v32, v32, v32 row_half_mirror row_mask:0xf bank_mask:0xf bound_ctrl:1
	s_nop 1
	v_add_f32_dpp v32, v32, v32 row_ror:8 row_mask:0xf bank_mask:0xf bound_ctrl:1
	s_nop 1
	v_add_f32_dpp v32, v32, v32 row_bcast:15 row_mask:0xf bank_mask:0xf bound_ctrl:1
	s_nop 1
	v_add_f32_dpp v32, v32, v32 row_bcast:31 row_mask:0xf bank_mask:0xf bound_ctrl:1
	s_nop 0
	v_readlane_b32 s24, v32, 63
	s_and_saveexec_b64 s[0:1], s[12:13]
	s_cbranch_execz .LBB0_595
	v_mad_i64_i32 v[46:47], s[26:27], s23, 24, v[24:25]
	v_mov_b32_e32 v32, s24
	global_store_dword v[46:47], v32, off sc1
; __device__ __forceinline__ u32 pack2(float lo, float hi) { return (u32)f2bf(lo) | ((u32)f2bf(hi) << 16); }
; __device__ __forceinline__ float wsum_u(float v) { return rdlane63(wsum_dpp63(v)); }
; __device__ __forceinline__ int opaque_tid() { int t = threadIdx.x; asm volatile("" : "+v"(t)); return t; }
; __device__ void rwprep_items(const Params& p, int l, unsigned char* ldsraw, int it_begin, int it_end, int it_step) {
;     ...
;       for (int tt = 0; tt < 4; ++tt) {
;         const int tok = tok0 + tt;
;         float r = pr_[tt + 1], k = pk_[tt + 1], v = pv_[tt + 1];
;         const float r1 = pr_[tt], k1 = pk_[tt], v1 = pv_[tt];
;         r += (r1 - r) * mur; k += (k1 - k) * muk; v += (v1 - v) * muv;
;         const float xw = w0c + aw[tt];
;         const float lw = -softplus_f(-xw) - 0.5f;
;         const float dec = __expf(-__expf(lw));
;         const float xa = a0c + aa[tt];
;         const float asig = 1.f / (1.f + __expf(-xa));
;         const float kkr = k * kkc;
;         const float ssum = wsum_u(kkr * kkr);
;         const float kk = kkr * rsqrtf(fmaxf(ssum, 1e-12f));
;         const float kmod = k * (1.f + (asig - 1.f) * kac);
;         const size_t o = ((size_t)tok * 384 + c) * 3;
;         rwp[o] = __float_as_uint(dec);
;         rwp[o + 1] = pack2(kk, kk * asig);
;         rwp[o + 2] = pack2(kmod, r);
;         const float bsum = wsum_u(r * kmod * rkc);
;         if ((tid & 63) == 0) bon[(size_t)tok * 6 + (tid >> 6)] = bsum;
;         vy[(size_t)tok * 384 + c] = f2bf(v);
;       }
; template <bool COOP>
; __global__ void __launch_bounds__(NT, 2) mega(Params p) {
;     ...
;             asm volatile("s_waitcnt vmcnt(0)" ::: "memory");
;             __syncthreads();
;             if (opaque_tid() == 0) {
;               __builtin_amdgcn_fence(__ATOMIC_RELEASE, "agent");
;               asm volatile("s_waitcnt vmcnt(0)" ::: "memory");
;               __hip_atomic_fetch_add(ctr + 512 + l * 256 + bb * 64 + tb, 1u, __ATOMIC_RELAXED, __HIP_MEMORY_SCOPE_AGENT);
;             }
.LBB0_595:
	s_or_b64 exec, exec, s[0:1]
	v_lshlrev_b32_e32 v45, 16, v5
	v_add_f32_e32 v5, v35, v57
	v_mul_f32_e64 v34, |v5|, s25
	v_lshlrev_b32_e32 v9, 16, v9
	v_exp_f32_e32 v42, v34
	v_sub_f32_e32 v32, v44, v9
	v_fma_f32 v32, v32, v49, v9
	v_bfe_u32 v34, v32, 16, 1
	v_add3_u32 v32, v32, v34, s96
	v_lshl_add_u64 v[34:35], v[40:41], 1, s[88:89]
	v_add_f32_e32 v40, 1.0, v42
	v_cmp_gt_f32_e32 vcc, s82, v40
	global_store_short_d16_hi v[34:35], v32, off sc1
	v_add_f32_e32 v33, v33, v56
	v_cndmask_b32_e64 v41, 0, 32, vcc
	v_ldexp_f32 v40, v40, v41
	v_log_f32_e32 v40, v40
	v_mul_f32_e32 v33, 0xbfb8aa3b, v33
	v_cndmask_b32_e32 v35, 0, v95, vcc
	v_exp_f32_e32 v33, v33
	v_mul_f32_e32 v34, 0x3f317217, v40
	v_fma_f32 v34, v40, s20, -v34
	v_fmac_f32_e32 v34, 0x3377d1cf, v40
	v_fmac_f32_e32 v34, 0x3f317217, v40
	v_cmp_lt_f32_e64 s[0:1], |v40|, s21
	v_max_f32_e64 v5, -v5, 0
	v_add_f32_e32 v33, 1.0, v33
	v_cndmask_b32_e64 v34, v40, v34, s[0:1]
	v_sub_f32_e32 v34, v34, v35
	v_add_f32_e32 v5, v5, v34
	v_sub_f32_e32 v5, -0.5, v5
	v_mul_f32_e32 v5, 0x3fb8aa3b, v5
	v_exp_f32_e32 v5, v5
	v_div_scale_f32 v35, s[0:1], v33, v33, 1.0
	v_rcp_f32_e32 v40, v35
	v_mul_f32_e32 v5, 0xbfb8aa3b, v5
	v_lshlrev_b32_e32 v38, 16, v48
	v_exp_f32_e32 v34, v5
	v_fma_f32 v5, -v35, v40, 1.0
	v_sub_f32_e32 v32, v43, v38
	v_fmac_f32_e32 v40, v5, v40
	v_div_scale_f32 v5, vcc, 1.0, v33, 1.0
	v_mul_f32_e32 v44, v32, v55
	v_mul_f32_e32 v32, v5, v40
	v_fma_f32 v41, -v35, v32, v5
	v_fmac_f32_e32 v32, v41, v40
	v_fma_f32 v5, -v35, v32, v5
	v_div_fmas_f32 v5, v5, v40, v32
	v_pk_add_f32 v[42:43], v[44:45], v[38:39]
	v_pk_add_f32 v[38:39], v[38:39], v[44:45] neg_lo:[0,1] neg_hi:[0,1]
	v_div_fixup_f32 v40, v5, v33, 1.0
	v_mov_b32_e32 v43, v39
	v_add_f32_e32 v5, -1.0, v40
	v_pk_mul_f32 v[38:39], v[42:43], v[36:37]
	v_fma_f32 v41, v54, v5, 1.0
	v_mul_f32_e32 v5, v38, v38
	v_mad_i64_i32 v[32:33], s[0:1], s22, v98, v[2:3]
	s_nop 0
	v_mov_b32_dpp v5, v5 quad_perm:[1,0,3,2] row_mask:0xf bank_mask:0xf bound_ctrl:1
	v_fmac_f32_e32 v5, v38, v38
	s_nop 1
	v_add_f32_dpp v5, v5, v5 quad_perm:[2,3,0,1] row_mask:0xf bank_mask:0xf bound_ctrl:1
	s_nop 1
	v_add_f32_dpp v5, v5, v5 row_half_mirror row_mask:0xf bank_mask:0xf bound_ctrl:1
	s_nop 1
	v_add_f32_dpp v5, v5, v5 row_ror:8 row_mask:0xf bank_mask:0xf bound_ctrl:1
	s_nop 1
	v_add_f32_dpp v5, v5, v5 row_bcast:15 row_mask:0xf bank_mask:0xf bound_ctrl:1
	s_nop 1
	v_add_f32_dpp v5, v5, v5 row_bcast:31 row_mask:0xf bank_mask:0xf bound_ctrl:1
	s_nop 0
	v_readlane_b32 s0, v5, 63
	s_nop 1
	v_max_f32_e64 v5, s0, s0
	v_max_f32_e32 v5, 0x2b8cbccc, v5
	v_rsq_f32_e32 v44, v5
	v_mad_u64_u32 v[46:47], s[0:1], v32, 12, s[84:85]
	v_mad_i32_i24 v47, v33, 12, v47
	v_pk_mul_f32 v[38:39], v[38:39], v[44:45]
	v_pk_fma_f32 v[36:37], v[42:43], v[36:37], v[44:45]
	v_mov_b32_e32 v39, v42
	v_pk_mul_f32 v[40:41], v[40:41], v[38:39]
	v_and_b32_sdwa v36, v37, v93 dst_sel:DWORD dst_unused:UNUSED_PAD src0_sel:WORD_1 src1_sel:DWORD
	v_and_b32_sdwa v35, v40, v93 dst_sel:DWORD dst_unused:UNUSED_PAD src0_sel:WORD_1 src1_sel:DWORD
	v_and_b32_sdwa v5, v41, v93 dst_sel:DWORD dst_unused:UNUSED_PAD src0_sel:WORD_1 src1_sel:DWORD
	v_add3_u32 v35, v40, v35, s96
	v_and_b32_sdwa v39, v38, v93 dst_sel:DWORD dst_unused:UNUSED_PAD src0_sel:WORD_1 src1_sel:DWORD
	v_add3_u32 v36, v37, v36, s96
	v_add3_u32 v5, v41, v5, s96
	v_and_b32_e32 v35, 0xffff0000, v35
	v_add3_u32 v38, v38, v39, s96
	v_and_b32_e32 v36, 0xffff0000, v36
	v_or_b32_sdwa v36, v5, v36 dst_sel:DWORD dst_unused:UNUSED_PAD src0_sel:WORD_1 src1_sel:DWORD
	v_or_b32_sdwa v35, v35, v38 dst_sel:DWORD dst_unused:UNUSED_PAD src0_sel:DWORD src1_sel:WORD_1
	v_mul_f32_e32 v5, v37, v41
	global_store_dwordx3 v[46:47], v[34:36], off sc1
	s_nop 1
	v_mul_f32_e32 v34, v50, v5
	s_nop 1
	v_mov_b32_dpp v34, v34 quad_perm:[1,0,3,2] row_mask:0xf bank_mask:0xf bound_ctrl:1
	v_fmac_f32_e32 v34, v50, v5
	s_nop 1
	v_add_f32_dpp v5, v34, v34 quad_perm:[2,3,0,1] row_mask:0xf bank_mask:0xf bound_ctrl:1
	s_nop 1
	v_add_f32_dpp v5, v5, v5 row_half_mirror row_mask:0xf bank_mask:0xf bound_ctrl:1
	s_nop 1
	v_add_f32_dpp v5, v5, v5 row_ror:8 row_mask:0xf bank_mask:0xf bound_ctrl:1
	s_nop 1
	v_add_f32_dpp v5, v5, v5 row_bcast:15 row_mask:0xf bank_mask:0xf bound_ctrl:1
	s_nop 1
	v_add_f32_dpp v5, v5, v5 row_bcast:31 row_mask:0xf bank_mask:0xf bound_ctrl:1
	s_nop 0
	v_readlane_b32 s23, v5, 63
	s_and_saveexec_b64 s[0:1], s[12:13]
	s_cbranch_execz .LBB0_576
	v_mad_i64_i32 v[34:35], s[24:25], s22, 24, v[24:25]
	v_mov_b32_e32 v5, s23
	global_store_dword v[34:35], v5, off sc1
	s_branch .LBB0_576
.LBB0_597:
	s_waitcnt vmcnt(0)
	v_mov_b32_e32 v0, v68
	s_barrier
	s_nop 0
	v_cmp_eq_u32_e32 vcc, 0, v0
	s_and_saveexec_b64 s[0:1], vcc
	s_cbranch_execz .LBB0_600
	s_mov_b64 s[6:7], exec
	v_mbcnt_lo_u32_b32 v0, s6, 0
	s_nop 0
	s_waitcnt vmcnt(0)
	s_waitcnt vmcnt(0)
	v_mbcnt_hi_u32_b32 v0, s7, v0
	v_cmp_eq_u32_e32 vcc, 0, v0
	s_and_b64 s[8:9], exec, vcc
	s_mov_b64 exec, s[8:9]
	s_cbranch_execz .LBB0_600
	s_lshl_b32 s8, s15, 8
	v_readlane_b32 s9, v160, 34
	s_add_u32 s10, s9, s8
	v_readlane_b32 s8, v160, 35
	s_addc_u32 s11, s8, 0
	s_ashr_i32 s15, s14, 31
	s_lshl_b64 s[8:9], s[14:15], 2
	s_add_u32 s8, s10, s8
	s_addc_u32 s9, s11, s9
	s_bcnt1_i32_b64 s6, s[6:7]
	v_mov_b32_e32 v0, s6
	global_atomic_add v1, v0, s[8:9] offset:2048
